# softmax sub/exp/add of tile t interleaved into the PV MFMA shadows of tile t-1 (both DA attention loops); arithmetic unchanged
# speedup vs baseline: 1.0013x; 1.0013x over previous
.LBB0_293:
	s_nop 8
	v_max_f32_e32 v0, v131, v131
	v_max_f32_e32 v187, v130, v130
	v_max_f32_e32 v0, v187, v0
	v_max_f32_e32 v187, v133, v133
	v_max_f32_e32 v188, v132, v132
	v_max_f32_e32 v187, v188, v187
	v_max_f32_e32 v188, v137, v137
	v_max_f32_e32 v189, v136, v136
	v_max_f32_e32 v188, v189, v188
	v_max3_f32 v188, v134, v135, v188
	v_max3_f32 v0, v0, v187, v188
	v_max_f32_e32 v187, v141, v141
	v_max_f32_e32 v188, v140, v140
	v_max_f32_e32 v187, v188, v187
	v_max_f32_e32 v188, v145, v145
	v_max_f32_e32 v189, v144, v144
	v_max_f32_e32 v188, v189, v188
	v_max3_f32 v187, v138, v139, v187
	v_max3_f32 v188, v142, v143, v188
	v_max3_f32 v0, v0, v187, v188
	v_mov_b32_e32 v187, v0
	s_nop 1
	v_permlane32_swap_b32_e32 v0, v187
	v_max_f32_e32 v187, v187, v187
	v_max_f32_e32 v0, v0, v0
	s_lshl_b32 s0, s49, 14
	v_max_f32_e32 v0, v0, v187
	v_add_f32_e32 v187, 0x41000000, v186
	s_add_i32 s3, s0, 0
	v_cmp_gt_f32_e32 vcc, v0, v187
	s_cmp_eq_u64 vcc, 0
	v_max_f32_e32 v187, v186, v186
	v_max_f32_e32 v0, v187, v0
	s_cselect_b64 s[0:1], -1, 0
	v_cndmask_b32_e64 v0, v0, v186, s[0:1]
	v_add_u32_e32 v252, s3, v224
	v_sub_f32_e32 v247, v186, v0
	v_add_u32_e32 v253, s3, v228
	ds_read_b64_tr_b16 v[186:187], v252 offset:49152
	ds_read_b64_tr_b16 v[188:189], v252 offset:53248
	ds_read_b64_tr_b16 v[190:191], v253 offset:49152
	ds_read_b64_tr_b16 v[192:193], v253 offset:53248
	v_exp_f32_e32 v247, v247
	v_add_u32_e32 v254, s3, v229
	ds_read_b64_tr_b16 v[248:249], v254 offset:49152
	ds_read_b64_tr_b16 v[250:251], v254 offset:53248
	s_setprio 1
	s_waitcnt lgkmcnt(4)
	v_mfma_f32_32x32x16_bf16 v[114:129], v[182:185], v[186:189], v[114:129]
	s_setprio 0
	v_add_u32_e32 v195, s3, v230
	ds_read_b64_tr_b16 v[186:187], v195 offset:49152
	ds_read_b64_tr_b16 v[188:189], v195 offset:53248
	v_sub_f32_e32 v130, v130, v0
	v_exp_f32_e32 v1, v130
	s_setprio 1
	s_waitcnt lgkmcnt(4)
	v_mfma_f32_32x32x16_bf16 v[98:113], v[182:185], v[190:193], v[98:113]
	s_setprio 0
	ds_read_b64_tr_b16 v[190:191], v252 offset:49408
	ds_read_b64_tr_b16 v[192:193], v252 offset:53504
	v_sub_f32_e32 v131, v131, v0
	v_exp_f32_e32 v131, v131
	v_add_f32_e32 v130, 0, v1
	s_setprio 1
	s_waitcnt lgkmcnt(4)
	v_mfma_f32_32x32x16_bf16 v[82:97], v[182:185], v[248:251], v[82:97]
	s_setprio 0
	ds_read_b64_tr_b16 v[248:249], v253 offset:49408
	ds_read_b64_tr_b16 v[250:251], v253 offset:53504
	v_sub_f32_e32 v132, v132, v0
	v_exp_f32_e32 v132, v132
	v_add_f32_e32 v130, v131, v130
	s_setprio 1
	s_waitcnt lgkmcnt(4)
	v_mfma_f32_32x32x16_bf16 v[66:81], v[182:185], v[186:189], v[66:81]
	s_setprio 0
	ds_read_b64_tr_b16 v[186:187], v254 offset:49408
	ds_read_b64_tr_b16 v[188:189], v254 offset:53504
	v_sub_f32_e32 v133, v133, v0
	v_exp_f32_e32 v133, v133
	v_add_f32_e32 v130, v132, v130
	s_setprio 1
	s_waitcnt lgkmcnt(4)
	v_mfma_f32_32x32x16_bf16 v[50:65], v[182:185], v[190:193], v[50:65]
	s_setprio 0
	ds_read_b64_tr_b16 v[190:191], v195 offset:49408
	ds_read_b64_tr_b16 v[192:193], v195 offset:53504
	v_sub_f32_e32 v134, v134, v0
	v_exp_f32_e32 v134, v134
	v_add_f32_e32 v130, v133, v130
	s_setprio 1
	s_waitcnt lgkmcnt(4)
	v_mfma_f32_32x32x16_bf16 v[34:49], v[182:185], v[248:251], v[34:49]
	s_setprio 0
	ds_read_b64_tr_b16 v[248:249], v252 offset:57344
	ds_read_b64_tr_b16 v[250:251], v252 offset:61440
	v_sub_f32_e32 v135, v135, v0
	v_exp_f32_e32 v135, v135
	v_add_f32_e32 v130, v134, v130
	s_setprio 1
	s_waitcnt lgkmcnt(4)
	v_mfma_f32_32x32x16_bf16 v[18:33], v[182:185], v[186:189], v[18:33]
	s_setprio 0
	ds_read_b64_tr_b16 v[186:187], v253 offset:57344
	ds_read_b64_tr_b16 v[188:189], v253 offset:61440
	v_sub_f32_e32 v136, v136, v0
	v_exp_f32_e32 v136, v136
	v_add_f32_e32 v130, v135, v130
	s_setprio 1
	s_waitcnt lgkmcnt(4)
	v_mfma_f32_32x32x16_bf16 v[2:17], v[182:185], v[190:193], v[2:17]
	s_setprio 0
	ds_read_b64_tr_b16 v[182:183], v254 offset:57344
	ds_read_b64_tr_b16 v[184:185], v254 offset:61440
	v_sub_f32_e32 v137, v137, v0
	v_exp_f32_e32 v137, v137
	v_add_f32_e32 v130, v136, v130
	s_setprio 1
	s_waitcnt lgkmcnt(4)
	v_mfma_f32_32x32x16_bf16 v[114:129], v[178:181], v[248:251], v[114:129]
	s_setprio 0
	ds_read_b64_tr_b16 v[190:191], v195 offset:57344
	ds_read_b64_tr_b16 v[192:193], v195 offset:61440
	v_sub_f32_e32 v138, v138, v0
	v_exp_f32_e32 v138, v138
	v_add_f32_e32 v130, v137, v130
	s_setprio 1
	s_waitcnt lgkmcnt(4)
	v_mfma_f32_32x32x16_bf16 v[98:113], v[178:181], v[186:189], v[98:113]
	s_setprio 0
	ds_read_b64_tr_b16 v[186:187], v252 offset:57600
	ds_read_b64_tr_b16 v[188:189], v252 offset:61696
	v_sub_f32_e32 v139, v139, v0
	v_exp_f32_e32 v139, v139
	v_add_f32_e32 v130, v138, v130
	s_setprio 1
	s_waitcnt lgkmcnt(4)
	v_mfma_f32_32x32x16_bf16 v[82:97], v[178:181], v[182:185], v[82:97]
	s_setprio 0
	ds_read_b64_tr_b16 v[182:183], v253 offset:57600
	ds_read_b64_tr_b16 v[184:185], v253 offset:61696
	v_sub_f32_e32 v140, v140, v0
	v_exp_f32_e32 v140, v140
	v_add_f32_e32 v130, v139, v130
	s_setprio 1
	s_waitcnt lgkmcnt(4)
	v_mfma_f32_32x32x16_bf16 v[66:81], v[178:181], v[190:193], v[66:81]
	s_setprio 0
	ds_read_b64_tr_b16 v[190:191], v254 offset:57600
	ds_read_b64_tr_b16 v[192:193], v254 offset:61696
	v_sub_f32_e32 v141, v141, v0
	v_exp_f32_e32 v141, v141
	v_add_f32_e32 v130, v140, v130
	s_setprio 1
	s_waitcnt lgkmcnt(4)
	v_mfma_f32_32x32x16_bf16 v[50:65], v[178:181], v[186:189], v[50:65]
	s_setprio 0
	ds_read_b64_tr_b16 v[186:187], v195 offset:57600
	ds_read_b64_tr_b16 v[188:189], v195 offset:61696
	v_sub_f32_e32 v142, v142, v0
	v_exp_f32_e32 v142, v142
	v_add_f32_e32 v130, v141, v130
	s_setprio 1
	s_waitcnt lgkmcnt(4)
	v_mfma_f32_32x32x16_bf16 v[34:49], v[178:181], v[182:185], v[34:49]
	s_setprio 0
	v_sub_f32_e32 v143, v143, v0
	v_exp_f32_e32 v143, v143
	v_add_f32_e32 v130, v142, v130
	s_setprio 1
	s_waitcnt lgkmcnt(2)
	v_mfma_f32_32x32x16_bf16 v[18:33], v[178:181], v[190:193], v[18:33]
	s_setprio 0
	v_sub_f32_e32 v144, v144, v0
	v_exp_f32_e32 v144, v144
	v_add_f32_e32 v130, v143, v130
	s_setprio 1
	s_waitcnt lgkmcnt(0)
	v_mfma_f32_32x32x16_bf16 v[2:17], v[178:181], v[186:189], v[2:17]
	s_setprio 0
	v_sub_f32_e32 v145, v145, v0
	v_exp_f32_e32 v145, v145
	v_add_f32_e32 v130, v144, v130
	s_cbranch_vccz .LBB0_295
	ds_write_b32 v226, v247
	ds_read_b128 v[190:193], v227 offset:96
	ds_read_b128 v[186:189], v227 offset:64
	ds_read_b128 v[182:185], v227 offset:32
	ds_read_b128 v[178:181], v227
	s_waitcnt lgkmcnt(3)
	v_pk_mul_f32 v[128:129], v[128:129], v[192:193]
	s_waitcnt lgkmcnt(2)
	v_pk_mul_f32 v[124:125], v[124:125], v[188:189]
	s_waitcnt lgkmcnt(1)
	v_pk_mul_f32 v[120:121], v[120:121], v[184:185]
	s_waitcnt lgkmcnt(0)
	v_pk_mul_f32 v[116:117], v[116:117], v[180:181]
	v_pk_mul_f32 v[126:127], v[126:127], v[190:191]
	v_pk_mul_f32 v[122:123], v[122:123], v[186:187]
	v_pk_mul_f32 v[118:119], v[118:119], v[182:183]
	v_pk_mul_f32 v[114:115], v[114:115], v[178:179]
	v_pk_mul_f32 v[112:113], v[112:113], v[192:193]
	v_pk_mul_f32 v[108:109], v[108:109], v[188:189]
	v_pk_mul_f32 v[104:105], v[104:105], v[184:185]
	v_pk_mul_f32 v[100:101], v[100:101], v[180:181]
	v_pk_mul_f32 v[110:111], v[110:111], v[190:191]
	v_pk_mul_f32 v[106:107], v[106:107], v[186:187]
	v_pk_mul_f32 v[102:103], v[102:103], v[182:183]
	v_pk_mul_f32 v[98:99], v[98:99], v[178:179]
	v_pk_mul_f32 v[96:97], v[96:97], v[192:193]
	v_pk_mul_f32 v[92:93], v[92:93], v[188:189]
	v_pk_mul_f32 v[88:89], v[88:89], v[184:185]
	v_pk_mul_f32 v[84:85], v[84:85], v[180:181]
	v_pk_mul_f32 v[94:95], v[94:95], v[190:191]
	v_pk_mul_f32 v[90:91], v[90:91], v[186:187]
	v_pk_mul_f32 v[86:87], v[86:87], v[182:183]
	v_pk_mul_f32 v[82:83], v[82:83], v[178:179]
	v_pk_mul_f32 v[80:81], v[80:81], v[192:193]
	v_pk_mul_f32 v[76:77], v[76:77], v[188:189]
	v_pk_mul_f32 v[72:73], v[72:73], v[184:185]
	v_pk_mul_f32 v[68:69], v[68:69], v[180:181]
	v_pk_mul_f32 v[78:79], v[78:79], v[190:191]
	v_pk_mul_f32 v[74:75], v[74:75], v[186:187]
	v_pk_mul_f32 v[70:71], v[70:71], v[182:183]
	v_pk_mul_f32 v[66:67], v[66:67], v[178:179]
	v_pk_mul_f32 v[64:65], v[64:65], v[192:193]
	v_pk_mul_f32 v[60:61], v[60:61], v[188:189]
	v_pk_mul_f32 v[56:57], v[56:57], v[184:185]
	v_pk_mul_f32 v[52:53], v[52:53], v[180:181]
	v_pk_mul_f32 v[62:63], v[62:63], v[190:191]
	v_pk_mul_f32 v[58:59], v[58:59], v[186:187]
	v_pk_mul_f32 v[54:55], v[54:55], v[182:183]
	v_pk_mul_f32 v[50:51], v[50:51], v[178:179]
	v_pk_mul_f32 v[48:49], v[48:49], v[192:193]
	v_pk_mul_f32 v[44:45], v[44:45], v[188:189]
	v_pk_mul_f32 v[40:41], v[40:41], v[184:185]
	v_pk_mul_f32 v[36:37], v[36:37], v[180:181]
	v_pk_mul_f32 v[46:47], v[46:47], v[190:191]
	v_pk_mul_f32 v[42:43], v[42:43], v[186:187]
	v_pk_mul_f32 v[38:39], v[38:39], v[182:183]
	v_pk_mul_f32 v[34:35], v[34:35], v[178:179]
	v_pk_mul_f32 v[32:33], v[32:33], v[192:193]
	v_pk_mul_f32 v[28:29], v[28:29], v[188:189]
	v_pk_mul_f32 v[24:25], v[24:25], v[184:185]
	v_pk_mul_f32 v[20:21], v[20:21], v[180:181]
	v_pk_mul_f32 v[30:31], v[30:31], v[190:191]
	v_pk_mul_f32 v[26:27], v[26:27], v[186:187]
	v_pk_mul_f32 v[22:23], v[22:23], v[182:183]
	v_pk_mul_f32 v[18:19], v[18:19], v[178:179]
	v_pk_mul_f32 v[16:17], v[16:17], v[192:193]
	v_pk_mul_f32 v[12:13], v[12:13], v[188:189]
	v_pk_mul_f32 v[8:9], v[8:9], v[184:185]
	v_pk_mul_f32 v[4:5], v[4:5], v[180:181]
	v_pk_mul_f32 v[14:15], v[14:15], v[190:191]
	v_pk_mul_f32 v[10:11], v[10:11], v[186:187]
	v_pk_mul_f32 v[6:7], v[6:7], v[182:183]
	v_pk_mul_f32 v[2:3], v[2:3], v[178:179]
.LBB0_295:
	v_add_f32_e32 v130, v145, v130
	s_add_i32 s0, s48, 1
	s_cmp_lg_u32 s48, 2
	s_cselect_b32 s0, s0, 0
	s_add_i32 s46, s46, 32
	s_add_i32 s47, s47, 1
	v_fmac_f32_e32 v130, v203, v247
	v_cvt_pk_bf16_f32 v182, v1, v131
	v_mov_b32_e32 v1, 0
	v_cvt_pk_bf16_f32 v183, v132, v133
	v_cvt_pk_bf16_f32 v184, v134, v135
	v_cvt_pk_bf16_f32 v185, v136, v137
	v_cvt_pk_bf16_f32 v178, v138, v139
	v_cvt_pk_bf16_f32 v179, v140, v141
	v_cvt_pk_bf16_f32 v180, v142, v143
	v_cvt_pk_bf16_f32 v181, v144, v145
	v_lshl_add_u64 v[204:205], v[204:205], 0, s[12:13]
	v_lshl_add_u64 v[206:207], v[206:207], 0, s[12:13]
	v_lshl_add_u64 v[208:209], v[208:209], 0, s[8:9]
	s_cmp_eq_u32 s45, s46
	v_lshl_add_u64 v[210:211], v[210:211], 0, s[8:9]
	s_cbranch_scc1 .LBB0_297
	v_mov_b32_e32 v203, v130
	v_mov_b32_e32 v186, v0
	s_mov_b32 s49, s48
	s_branch .LBB0_281

.LBB0_1617:
	s_nop 8
	v_max_f32_e32 v0, v131, v131
	v_max_f32_e32 v187, v130, v130
	v_max_f32_e32 v0, v187, v0
	v_max_f32_e32 v187, v133, v133
	v_max_f32_e32 v188, v132, v132
	v_max_f32_e32 v187, v188, v187
	v_max_f32_e32 v188, v137, v137
	v_max_f32_e32 v189, v136, v136
	v_max_f32_e32 v188, v189, v188
	v_max3_f32 v188, v134, v135, v188
	v_max3_f32 v0, v0, v187, v188
	v_max_f32_e32 v187, v141, v141
	v_max_f32_e32 v188, v140, v140
	v_max_f32_e32 v187, v188, v187
	v_max_f32_e32 v188, v145, v145
	v_max_f32_e32 v189, v144, v144
	v_max_f32_e32 v188, v189, v188
	v_max3_f32 v187, v138, v139, v187
	v_max3_f32 v188, v142, v143, v188
	v_max3_f32 v0, v0, v187, v188
	v_mov_b32_e32 v187, v0
	s_nop 1
	v_permlane32_swap_b32_e32 v0, v187
	v_max_f32_e32 v187, v187, v187
	v_max_f32_e32 v0, v0, v0
	s_lshl_b32 s0, s47, 14
	v_max_f32_e32 v0, v0, v187
	v_add_f32_e32 v187, 0x41000000, v186
	s_add_i32 s3, s0, 0
	v_cmp_gt_f32_e32 vcc, v0, v187
	s_cmp_eq_u64 vcc, 0
	v_max_f32_e32 v187, v186, v186
	v_max_f32_e32 v0, v187, v0
	s_cselect_b64 s[0:1], -1, 0
	v_cndmask_b32_e64 v0, v0, v186, s[0:1]
	v_add_u32_e32 v252, s3, v224
	v_sub_f32_e32 v247, v186, v0
	v_add_u32_e32 v253, s3, v228
	ds_read_b64_tr_b16 v[186:187], v252 offset:49152
	ds_read_b64_tr_b16 v[188:189], v252 offset:53248
	ds_read_b64_tr_b16 v[190:191], v253 offset:49152
	ds_read_b64_tr_b16 v[192:193], v253 offset:53248
	v_exp_f32_e32 v247, v247
	v_add_u32_e32 v254, s3, v229
	ds_read_b64_tr_b16 v[248:249], v254 offset:49152
	ds_read_b64_tr_b16 v[250:251], v254 offset:53248
	s_setprio 1
	s_waitcnt lgkmcnt(4)
	v_mfma_f32_32x32x16_bf16 v[114:129], v[182:185], v[186:189], v[114:129]
	s_setprio 0
	v_add_u32_e32 v195, s3, v230
	ds_read_b64_tr_b16 v[186:187], v195 offset:49152
	ds_read_b64_tr_b16 v[188:189], v195 offset:53248
	v_sub_f32_e32 v130, v130, v0
	v_exp_f32_e32 v1, v130
	s_setprio 1
	s_waitcnt lgkmcnt(4)
	v_mfma_f32_32x32x16_bf16 v[98:113], v[182:185], v[190:193], v[98:113]
	s_setprio 0
	ds_read_b64_tr_b16 v[190:191], v252 offset:49408
	ds_read_b64_tr_b16 v[192:193], v252 offset:53504
	v_sub_f32_e32 v131, v131, v0
	v_exp_f32_e32 v131, v131
	v_add_f32_e32 v130, 0, v1
	s_setprio 1
	s_waitcnt lgkmcnt(4)
	v_mfma_f32_32x32x16_bf16 v[82:97], v[182:185], v[248:251], v[82:97]
	s_setprio 0
	ds_read_b64_tr_b16 v[248:249], v253 offset:49408
	ds_read_b64_tr_b16 v[250:251], v253 offset:53504
	v_sub_f32_e32 v132, v132, v0
	v_exp_f32_e32 v132, v132
	v_add_f32_e32 v130, v131, v130
	s_setprio 1
	s_waitcnt lgkmcnt(4)
	v_mfma_f32_32x32x16_bf16 v[66:81], v[182:185], v[186:189], v[66:81]
	s_setprio 0
	ds_read_b64_tr_b16 v[186:187], v254 offset:49408
	ds_read_b64_tr_b16 v[188:189], v254 offset:53504
	v_sub_f32_e32 v133, v133, v0
	v_exp_f32_e32 v133, v133
	v_add_f32_e32 v130, v132, v130
	s_setprio 1
	s_waitcnt lgkmcnt(4)
	v_mfma_f32_32x32x16_bf16 v[50:65], v[182:185], v[190:193], v[50:65]
	s_setprio 0
	ds_read_b64_tr_b16 v[190:191], v195 offset:49408
	ds_read_b64_tr_b16 v[192:193], v195 offset:53504
	v_sub_f32_e32 v134, v134, v0
	v_exp_f32_e32 v134, v134
	v_add_f32_e32 v130, v133, v130
	s_setprio 1
	s_waitcnt lgkmcnt(4)
	v_mfma_f32_32x32x16_bf16 v[34:49], v[182:185], v[248:251], v[34:49]
	s_setprio 0
	ds_read_b64_tr_b16 v[248:249], v252 offset:57344
	ds_read_b64_tr_b16 v[250:251], v252 offset:61440
	v_sub_f32_e32 v135, v135, v0
	v_exp_f32_e32 v135, v135
	v_add_f32_e32 v130, v134, v130
	s_setprio 1
	s_waitcnt lgkmcnt(4)
	v_mfma_f32_32x32x16_bf16 v[18:33], v[182:185], v[186:189], v[18:33]
	s_setprio 0
	ds_read_b64_tr_b16 v[186:187], v253 offset:57344
	ds_read_b64_tr_b16 v[188:189], v253 offset:61440
	v_sub_f32_e32 v136, v136, v0
	v_exp_f32_e32 v136, v136
	v_add_f32_e32 v130, v135, v130
	s_setprio 1
	s_waitcnt lgkmcnt(4)
	v_mfma_f32_32x32x16_bf16 v[2:17], v[182:185], v[190:193], v[2:17]
	s_setprio 0
	ds_read_b64_tr_b16 v[182:183], v254 offset:57344
	ds_read_b64_tr_b16 v[184:185], v254 offset:61440
	v_sub_f32_e32 v137, v137, v0
	v_exp_f32_e32 v137, v137
	v_add_f32_e32 v130, v136, v130
	s_setprio 1
	s_waitcnt lgkmcnt(4)
	v_mfma_f32_32x32x16_bf16 v[114:129], v[178:181], v[248:251], v[114:129]
	s_setprio 0
	ds_read_b64_tr_b16 v[190:191], v195 offset:57344
	ds_read_b64_tr_b16 v[192:193], v195 offset:61440
	v_sub_f32_e32 v138, v138, v0
	v_exp_f32_e32 v138, v138
	v_add_f32_e32 v130, v137, v130
	s_setprio 1
	s_waitcnt lgkmcnt(4)
	v_mfma_f32_32x32x16_bf16 v[98:113], v[178:181], v[186:189], v[98:113]
	s_setprio 0
	ds_read_b64_tr_b16 v[186:187], v252 offset:57600
	ds_read_b64_tr_b16 v[188:189], v252 offset:61696
	v_sub_f32_e32 v139, v139, v0
	v_exp_f32_e32 v139, v139
	v_add_f32_e32 v130, v138, v130
	s_setprio 1
	s_waitcnt lgkmcnt(4)
	v_mfma_f32_32x32x16_bf16 v[82:97], v[178:181], v[182:185], v[82:97]
	s_setprio 0
	ds_read_b64_tr_b16 v[182:183], v253 offset:57600
	ds_read_b64_tr_b16 v[184:185], v253 offset:61696
	v_sub_f32_e32 v140, v140, v0
	v_exp_f32_e32 v140, v140
	v_add_f32_e32 v130, v139, v130
	s_setprio 1
	s_waitcnt lgkmcnt(4)
	v_mfma_f32_32x32x16_bf16 v[66:81], v[178:181], v[190:193], v[66:81]
	s_setprio 0
	ds_read_b64_tr_b16 v[190:191], v254 offset:57600
	ds_read_b64_tr_b16 v[192:193], v254 offset:61696
	v_sub_f32_e32 v141, v141, v0
	v_exp_f32_e32 v141, v141
	v_add_f32_e32 v130, v140, v130
	s_setprio 1
	s_waitcnt lgkmcnt(4)
	v_mfma_f32_32x32x16_bf16 v[50:65], v[178:181], v[186:189], v[50:65]
	s_setprio 0
	ds_read_b64_tr_b16 v[186:187], v195 offset:57600
	ds_read_b64_tr_b16 v[188:189], v195 offset:61696
	v_sub_f32_e32 v142, v142, v0
	v_exp_f32_e32 v142, v142
	v_add_f32_e32 v130, v141, v130
	s_setprio 1
	s_waitcnt lgkmcnt(4)
	v_mfma_f32_32x32x16_bf16 v[34:49], v[178:181], v[182:185], v[34:49]
	s_setprio 0
	v_sub_f32_e32 v143, v143, v0
	v_exp_f32_e32 v143, v143
	v_add_f32_e32 v130, v142, v130
	s_setprio 1
	s_waitcnt lgkmcnt(2)
	v_mfma_f32_32x32x16_bf16 v[18:33], v[178:181], v[190:193], v[18:33]
	s_setprio 0
	v_sub_f32_e32 v144, v144, v0
	v_exp_f32_e32 v144, v144
	v_add_f32_e32 v130, v143, v130
	s_setprio 1
	s_waitcnt lgkmcnt(0)
	v_mfma_f32_32x32x16_bf16 v[2:17], v[178:181], v[186:189], v[2:17]
	s_setprio 0
	v_sub_f32_e32 v145, v145, v0
	v_exp_f32_e32 v145, v145
	v_add_f32_e32 v130, v144, v130
	s_cbranch_vccz .LBB0_1619
	ds_write_b32 v226, v247
	ds_read_b128 v[190:193], v227 offset:96
	ds_read_b128 v[186:189], v227 offset:64
	ds_read_b128 v[182:185], v227 offset:32
	ds_read_b128 v[178:181], v227
	s_waitcnt lgkmcnt(3)
	v_pk_mul_f32 v[128:129], v[128:129], v[192:193]
	s_waitcnt lgkmcnt(2)
	v_pk_mul_f32 v[124:125], v[124:125], v[188:189]
	s_waitcnt lgkmcnt(1)
	v_pk_mul_f32 v[120:121], v[120:121], v[184:185]
	s_waitcnt lgkmcnt(0)
	v_pk_mul_f32 v[116:117], v[116:117], v[180:181]
	v_pk_mul_f32 v[126:127], v[126:127], v[190:191]
	v_pk_mul_f32 v[122:123], v[122:123], v[186:187]
	v_pk_mul_f32 v[118:119], v[118:119], v[182:183]
	v_pk_mul_f32 v[114:115], v[114:115], v[178:179]
	v_pk_mul_f32 v[112:113], v[112:113], v[192:193]
	v_pk_mul_f32 v[108:109], v[108:109], v[188:189]
	v_pk_mul_f32 v[104:105], v[104:105], v[184:185]
	v_pk_mul_f32 v[100:101], v[100:101], v[180:181]
	v_pk_mul_f32 v[110:111], v[110:111], v[190:191]
	v_pk_mul_f32 v[106:107], v[106:107], v[186:187]
	v_pk_mul_f32 v[102:103], v[102:103], v[182:183]
	v_pk_mul_f32 v[98:99], v[98:99], v[178:179]
	v_pk_mul_f32 v[96:97], v[96:97], v[192:193]
	v_pk_mul_f32 v[92:93], v[92:93], v[188:189]
	v_pk_mul_f32 v[88:89], v[88:89], v[184:185]
	v_pk_mul_f32 v[84:85], v[84:85], v[180:181]
	v_pk_mul_f32 v[94:95], v[94:95], v[190:191]
	v_pk_mul_f32 v[90:91], v[90:91], v[186:187]
	v_pk_mul_f32 v[86:87], v[86:87], v[182:183]
	v_pk_mul_f32 v[82:83], v[82:83], v[178:179]
	v_pk_mul_f32 v[80:81], v[80:81], v[192:193]
	v_pk_mul_f32 v[76:77], v[76:77], v[188:189]
	v_pk_mul_f32 v[72:73], v[72:73], v[184:185]
	v_pk_mul_f32 v[68:69], v[68:69], v[180:181]
	v_pk_mul_f32 v[78:79], v[78:79], v[190:191]
	v_pk_mul_f32 v[74:75], v[74:75], v[186:187]
	v_pk_mul_f32 v[70:71], v[70:71], v[182:183]
	v_pk_mul_f32 v[66:67], v[66:67], v[178:179]
	v_pk_mul_f32 v[64:65], v[64:65], v[192:193]
	v_pk_mul_f32 v[60:61], v[60:61], v[188:189]
	v_pk_mul_f32 v[56:57], v[56:57], v[184:185]
	v_pk_mul_f32 v[52:53], v[52:53], v[180:181]
	v_pk_mul_f32 v[62:63], v[62:63], v[190:191]
	v_pk_mul_f32 v[58:59], v[58:59], v[186:187]
	v_pk_mul_f32 v[54:55], v[54:55], v[182:183]
	v_pk_mul_f32 v[50:51], v[50:51], v[178:179]
	v_pk_mul_f32 v[48:49], v[48:49], v[192:193]
	v_pk_mul_f32 v[44:45], v[44:45], v[188:189]
	v_pk_mul_f32 v[40:41], v[40:41], v[184:185]
	v_pk_mul_f32 v[36:37], v[36:37], v[180:181]
	v_pk_mul_f32 v[46:47], v[46:47], v[190:191]
	v_pk_mul_f32 v[42:43], v[42:43], v[186:187]
	v_pk_mul_f32 v[38:39], v[38:39], v[182:183]
	v_pk_mul_f32 v[34:35], v[34:35], v[178:179]
	v_pk_mul_f32 v[32:33], v[32:33], v[192:193]
	v_pk_mul_f32 v[28:29], v[28:29], v[188:189]
	v_pk_mul_f32 v[24:25], v[24:25], v[184:185]
	v_pk_mul_f32 v[20:21], v[20:21], v[180:181]
	v_pk_mul_f32 v[30:31], v[30:31], v[190:191]
	v_pk_mul_f32 v[26:27], v[26:27], v[186:187]
	v_pk_mul_f32 v[22:23], v[22:23], v[182:183]
	v_pk_mul_f32 v[18:19], v[18:19], v[178:179]
	v_pk_mul_f32 v[16:17], v[16:17], v[192:193]
	v_pk_mul_f32 v[12:13], v[12:13], v[188:189]
	v_pk_mul_f32 v[8:9], v[8:9], v[184:185]
	v_pk_mul_f32 v[4:5], v[4:5], v[180:181]
	v_pk_mul_f32 v[14:15], v[14:15], v[190:191]
	v_pk_mul_f32 v[10:11], v[10:11], v[186:187]
	v_pk_mul_f32 v[6:7], v[6:7], v[182:183]
	v_pk_mul_f32 v[2:3], v[2:3], v[178:179]
.LBB0_1619:
	v_add_f32_e32 v130, v145, v130
	s_add_i32 s0, s46, 1
	s_cmp_lg_u32 s46, 2
	s_cselect_b32 s0, s0, 0
	s_add_i32 s44, s44, 32
	s_add_i32 s45, s45, 1
	v_fmac_f32_e32 v130, v203, v247
	v_cvt_pk_bf16_f32 v182, v1, v131
	v_mov_b32_e32 v1, 0
	v_cvt_pk_bf16_f32 v183, v132, v133
	v_cvt_pk_bf16_f32 v184, v134, v135
	v_cvt_pk_bf16_f32 v185, v136, v137
	v_cvt_pk_bf16_f32 v178, v138, v139
	v_cvt_pk_bf16_f32 v179, v140, v141
	v_cvt_pk_bf16_f32 v180, v142, v143
	v_cvt_pk_bf16_f32 v181, v144, v145
	v_lshl_add_u64 v[204:205], v[204:205], 0, s[12:13]
	v_lshl_add_u64 v[206:207], v[206:207], 0, s[12:13]
	v_lshl_add_u64 v[208:209], v[208:209], 0, s[8:9]
	s_cmp_eq_u32 s43, s44
	v_lshl_add_u64 v[210:211], v[210:211], 0, s[8:9]
	s_cbranch_scc1 .LBB0_1621
	v_mov_b32_e32 v203, v130
	v_mov_b32_e32 v186, v0
	s_mov_b32 s47, s46
	s_branch .LBB0_1605
